# leading half starts its epilogue (up: first SwiGLU piece; residual: base-load issue) before the ALIGN barrier; on top of v78
# speedup vs baseline: 1.0099x; 1.0099x over previous
; #define PG8_GAS __attribute__((address_space(1)))
; __device__ __forceinline__ unsigned cvtpk(float lo, float hi) { f32x2 v = {lo, hi}; bf16x2_t b = __builtin_convertvector(v, bf16x2_t); return __builtin_bit_cast(unsigned, b); }
; __device__ __forceinline__ float silu_mul(float g, float u) { return g * u * __builtin_amdgcn_rcpf(1.0f + __builtin_amdgcn_exp2f(-1.4426950408889634f * g)); }
; #define PG8_BAR __builtin_amdgcn_s_barrier()
;     __device__ __forceinline__ void operator()(const f32x4 (&acc)[2][2][4][2], const Unit& u, int wr, int wc, int fr, int fq) const {
;         const int row0 = u.pm * BM + wr * 64 + fr, col0 = u.pn * HALF + wc * 32 + 8 * fq;
; #pragma unroll
;         for (int ai = 0; ai < 2; ++ai)
; #pragma unroll
;             for (int m = 0; m < 4; ++m) {
;                 bf16_t* p = O + (size_t)(row0 + ai * HALF + m * 16) * ldc + col0;
;                 const f32x4 g0 = acc[ai][0][m][0], g1 = acc[ai][0][m][1], u0 = acc[ai][1][m][0], u1 = acc[ai][1][m][1];
;                 u32x4 w;
;                 w.x = cvtpk(silu_mul(g0[0], u0[0]), silu_mul(g0[1], u0[1])); w.y = cvtpk(silu_mul(g0[2], u0[2]), silu_mul(g0[3], u0[3]));
;                 w.z = cvtpk(silu_mul(g1[0], u1[0]), silu_mul(g1[1], u1[1])); w.w = cvtpk(silu_mul(g1[2], u1[2]), silu_mul(g1[3], u1[3]));
;                 __builtin_nontemporal_store(w, (PG8_GAS u32x4*)p);
;             }
; template <class Epi, class Sched, bool ALIGN_EPI = false, bool SP2 = false>
; __device__ __forceinline__ void gemm_phase(PG8_LAS unsigned char* lds, const Gemm g, const Sched& S, const Epi& E, const int tid) {
;     ...
;         if constexpr (ALIGN_EPI) { if (wr == 0) PG8_BAR; }
.LBB0_191:
	s_mov_b32 s54, 0xbfb8aa3b
	s_mov_b32 s55, 0xbfb8aa3b
	v_lshl_add_u32 v149, s33, 8, v5
	v_lshl_or_b32 v144, s31, 7, v147
	v_ashrrev_i32_e32 v145, 31, v144
	v_mov_b64_e32 v[142:143], s[6:7]
	v_mad_i64_i32 v[150:151], s[36:37], v149, s93, v[142:143]
	v_lshlrev_b64 v[144:145], 1, v[144:145]
	v_mov_b32_e32 v156, 0x16000
	v_mov_b32_e32 v158, 0x6e000
	v_mov_b32_e32 v157, 0
	v_mov_b32_e32 v159, 0
	v_lshl_add_u64 v[150:151], v[150:151], 0, v[144:145]
	v_pk_mul_f32 v[152:153], v[126:127], s[54:55]
	v_pk_mul_f32 v[154:155], v[128:129], s[54:55]
	v_exp_f32_e32 v152, v152
	v_exp_f32_e32 v153, v153
	v_exp_f32_e32 v154, v154
	v_exp_f32_e32 v155, v155
	v_pk_mul_f32 v[126:127], v[126:127], v[130:131]
	v_pk_mul_f32 v[128:129], v[128:129], v[132:133]
	v_pk_add_f32 v[152:153], v[152:153], 1.0 op_sel_hi:[1,0]
	v_pk_add_f32 v[154:155], v[154:155], 1.0 op_sel_hi:[1,0]
	v_rcp_f32_e32 v152, v152
	v_rcp_f32_e32 v153, v153
	v_rcp_f32_e32 v154, v154
	v_rcp_f32_e32 v155, v155
	v_pk_mul_f32 v[126:127], v[152:153], v[126:127]
	v_pk_mul_f32 v[128:129], v[154:155], v[128:129]
	v_cvt_pk_bf16_f32 v126, v126, v127
	v_cvt_pk_bf16_f32 v127, v128, v129
	v_pk_mul_f32 v[152:153], v[118:119], s[54:55]
	v_pk_mul_f32 v[154:155], v[120:121], s[54:55]
	v_exp_f32_e32 v152, v152
	v_exp_f32_e32 v153, v153
	v_exp_f32_e32 v154, v154
	v_exp_f32_e32 v155, v155
	v_pk_mul_f32 v[118:119], v[118:119], v[122:123]
	v_pk_mul_f32 v[120:121], v[120:121], v[124:125]
	v_pk_add_f32 v[152:153], v[152:153], 1.0 op_sel_hi:[1,0]
	v_pk_add_f32 v[154:155], v[154:155], 1.0 op_sel_hi:[1,0]
	v_rcp_f32_e32 v152, v152
	v_rcp_f32_e32 v153, v153
	v_rcp_f32_e32 v154, v154
	v_rcp_f32_e32 v155, v155
	v_pk_mul_f32 v[118:119], v[152:153], v[118:119]
	v_pk_mul_f32 v[120:121], v[154:155], v[120:121]
	v_cvt_pk_bf16_f32 v128, v118, v119
	v_cvt_pk_bf16_f32 v129, v120, v121
	global_store_dwordx4 v[150:151], v[126:129], off nt
	v_lshl_add_u64 v[150:151], v[150:151], 0, v[156:157]
	s_cmp_eq_u64 s[72:73], 0
	s_cbranch_scc1 .Lup_epi_nobar
	s_barrier
.Lup_epi_nobar:
	v_pk_mul_f32 v[152:153], v[110:111], s[54:55]
	v_pk_mul_f32 v[154:155], v[112:113], s[54:55]
	v_exp_f32_e32 v152, v152
	v_exp_f32_e32 v153, v153
	v_exp_f32_e32 v154, v154
	v_exp_f32_e32 v155, v155
	v_pk_mul_f32 v[110:111], v[110:111], v[114:115]
	v_pk_mul_f32 v[112:113], v[112:113], v[116:117]
	v_pk_add_f32 v[152:153], v[152:153], 1.0 op_sel_hi:[1,0]
	v_pk_add_f32 v[154:155], v[154:155], 1.0 op_sel_hi:[1,0]
	v_rcp_f32_e32 v152, v152
	v_rcp_f32_e32 v153, v153
	v_rcp_f32_e32 v154, v154
	v_rcp_f32_e32 v155, v155
	v_pk_mul_f32 v[110:111], v[152:153], v[110:111]
	v_pk_mul_f32 v[112:113], v[154:155], v[112:113]
	v_cvt_pk_bf16_f32 v110, v110, v111
	v_cvt_pk_bf16_f32 v111, v112, v113
	v_pk_mul_f32 v[152:153], v[102:103], s[54:55]
	v_pk_mul_f32 v[154:155], v[104:105], s[54:55]
	v_exp_f32_e32 v152, v152
	v_exp_f32_e32 v153, v153
	v_exp_f32_e32 v154, v154
	v_exp_f32_e32 v155, v155
	v_pk_mul_f32 v[102:103], v[102:103], v[106:107]
	v_pk_mul_f32 v[104:105], v[104:105], v[108:109]
	v_pk_add_f32 v[152:153], v[152:153], 1.0 op_sel_hi:[1,0]
	v_pk_add_f32 v[154:155], v[154:155], 1.0 op_sel_hi:[1,0]
	v_rcp_f32_e32 v152, v152
	v_rcp_f32_e32 v153, v153
	v_rcp_f32_e32 v154, v154
	v_rcp_f32_e32 v155, v155
	v_pk_mul_f32 v[102:103], v[152:153], v[102:103]
	v_pk_mul_f32 v[104:105], v[154:155], v[104:105]
	v_cvt_pk_bf16_f32 v112, v102, v103
	v_cvt_pk_bf16_f32 v113, v104, v105
	global_store_dwordx4 v[150:151], v[110:113], off nt
	v_lshl_add_u64 v[150:151], v[150:151], 0, v[156:157]
	v_pk_mul_f32 v[152:153], v[94:95], s[54:55]
	v_pk_mul_f32 v[154:155], v[96:97], s[54:55]
	v_exp_f32_e32 v152, v152
	v_exp_f32_e32 v153, v153
	v_exp_f32_e32 v154, v154
	v_exp_f32_e32 v155, v155
	v_pk_mul_f32 v[94:95], v[94:95], v[98:99]
	v_pk_mul_f32 v[96:97], v[96:97], v[100:101]
	v_pk_add_f32 v[152:153], v[152:153], 1.0 op_sel_hi:[1,0]
	v_pk_add_f32 v[154:155], v[154:155], 1.0 op_sel_hi:[1,0]
	v_rcp_f32_e32 v152, v152
	v_rcp_f32_e32 v153, v153
	v_rcp_f32_e32 v154, v154
	v_rcp_f32_e32 v155, v155
	v_pk_mul_f32 v[94:95], v[152:153], v[94:95]
	v_pk_mul_f32 v[96:97], v[154:155], v[96:97]
	v_cvt_pk_bf16_f32 v94, v94, v95
	v_cvt_pk_bf16_f32 v95, v96, v97
	v_pk_mul_f32 v[152:153], v[86:87], s[54:55]
	v_pk_mul_f32 v[154:155], v[88:89], s[54:55]
	v_exp_f32_e32 v152, v152
	v_exp_f32_e32 v153, v153
	v_exp_f32_e32 v154, v154
	v_exp_f32_e32 v155, v155
	v_pk_mul_f32 v[86:87], v[86:87], v[90:91]
	v_pk_mul_f32 v[88:89], v[88:89], v[92:93]
	v_pk_add_f32 v[152:153], v[152:153], 1.0 op_sel_hi:[1,0]
	v_pk_add_f32 v[154:155], v[154:155], 1.0 op_sel_hi:[1,0]
	v_rcp_f32_e32 v152, v152
	v_rcp_f32_e32 v153, v153
	v_rcp_f32_e32 v154, v154
	v_rcp_f32_e32 v155, v155
	v_pk_mul_f32 v[86:87], v[152:153], v[86:87]
	v_pk_mul_f32 v[88:89], v[154:155], v[88:89]
	v_cvt_pk_bf16_f32 v96, v86, v87
	v_cvt_pk_bf16_f32 v97, v88, v89
	global_store_dwordx4 v[150:151], v[94:97], off nt
	v_lshl_add_u64 v[150:151], v[150:151], 0, v[156:157]
	v_pk_mul_f32 v[152:153], v[78:79], s[54:55]
	v_pk_mul_f32 v[154:155], v[80:81], s[54:55]
	v_exp_f32_e32 v152, v152
	v_exp_f32_e32 v153, v153
	v_exp_f32_e32 v154, v154
	v_exp_f32_e32 v155, v155
	v_pk_mul_f32 v[78:79], v[78:79], v[82:83]
	v_pk_mul_f32 v[80:81], v[80:81], v[84:85]
	v_pk_add_f32 v[152:153], v[152:153], 1.0 op_sel_hi:[1,0]
	v_pk_add_f32 v[154:155], v[154:155], 1.0 op_sel_hi:[1,0]
	v_rcp_f32_e32 v152, v152
	v_rcp_f32_e32 v153, v153
	v_rcp_f32_e32 v154, v154
	v_rcp_f32_e32 v155, v155
	v_pk_mul_f32 v[78:79], v[152:153], v[78:79]
	v_pk_mul_f32 v[80:81], v[154:155], v[80:81]
	v_cvt_pk_bf16_f32 v78, v78, v79
	v_cvt_pk_bf16_f32 v79, v80, v81
	v_pk_mul_f32 v[152:153], v[70:71], s[54:55]
; #define PG8_GAS __attribute__((address_space(1)))
; __device__ __forceinline__ unsigned cvtpk(float lo, float hi) { f32x2 v = {lo, hi}; bf16x2_t b = __builtin_convertvector(v, bf16x2_t); return __builtin_bit_cast(unsigned, b); }
; __device__ __forceinline__ float silu_mul(float g, float u) { return g * u * __builtin_amdgcn_rcpf(1.0f + __builtin_amdgcn_exp2f(-1.4426950408889634f * g)); }
; #define PG8_BAR __builtin_amdgcn_s_barrier()
;     __device__ __forceinline__ void operator()(const f32x4 (&acc)[2][2][4][2], const Unit& u, int wr, int wc, int fr, int fq) const {
;     ...
;         for (int ai = 0; ai < 2; ++ai)
; #pragma unroll
;             for (int m = 0; m < 4; ++m) {
;                 bf16_t* p = O + (size_t)(row0 + ai * HALF + m * 16) * ldc + col0;
;                 const f32x4 g0 = acc[ai][0][m][0], g1 = acc[ai][0][m][1], u0 = acc[ai][1][m][0], u1 = acc[ai][1][m][1];
;                 u32x4 w;
;                 w.x = cvtpk(silu_mul(g0[0], u0[0]), silu_mul(g0[1], u0[1])); w.y = cvtpk(silu_mul(g0[2], u0[2]), silu_mul(g0[3], u0[3]));
;                 w.z = cvtpk(silu_mul(g1[0], u1[0]), silu_mul(g1[1], u1[1])); w.w = cvtpk(silu_mul(g1[2], u1[2]), silu_mul(g1[3], u1[3]));
;                 __builtin_nontemporal_store(w, (PG8_GAS u32x4*)p);
;             }
; template <class Epi, class Sched, bool ALIGN_EPI = false, bool SP2 = false>
; __device__ __forceinline__ void gemm_phase(PG8_LAS unsigned char* lds, const Gemm g, const Sched& S, const Epi& E, const int tid) {
;     ...
;         if (!has_next) break;
; #pragma unroll
;         for (int a = 0; a < 2; ++a)
; #pragma unroll
;             for (int b = 0; b < 2; ++b)
; #pragma unroll
;                 for (int m = 0; m < 4; ++m)
; #pragma unroll
;                     for (int n = 0; n < 2; ++n) acc[a][b][m][n] = (f32x4){0.f, 0.f, 0.f, 0.f};
;         cur = nxt; cA = nA; cB = nB; ++ui;
;         if constexpr (ALIGN_EPI) { if (wr == 1) PG8_BAR; }
;     }
	v_pk_mul_f32 v[154:155], v[72:73], s[54:55]
	v_exp_f32_e32 v152, v152
	v_exp_f32_e32 v153, v153
	v_exp_f32_e32 v154, v154
	v_exp_f32_e32 v155, v155
	v_pk_mul_f32 v[70:71], v[70:71], v[74:75]
	v_pk_mul_f32 v[72:73], v[72:73], v[76:77]
	v_pk_add_f32 v[152:153], v[152:153], 1.0 op_sel_hi:[1,0]
	v_pk_add_f32 v[154:155], v[154:155], 1.0 op_sel_hi:[1,0]
	v_rcp_f32_e32 v152, v152
	v_rcp_f32_e32 v153, v153
	v_rcp_f32_e32 v154, v154
	v_rcp_f32_e32 v155, v155
	v_pk_mul_f32 v[70:71], v[152:153], v[70:71]
	v_pk_mul_f32 v[72:73], v[154:155], v[72:73]
	v_cvt_pk_bf16_f32 v80, v70, v71
	v_cvt_pk_bf16_f32 v81, v72, v73
	global_store_dwordx4 v[150:151], v[78:81], off nt
	v_lshl_add_u64 v[150:151], v[150:151], 0, v[158:159]
	v_pk_mul_f32 v[152:153], v[62:63], s[54:55]
	v_pk_mul_f32 v[154:155], v[64:65], s[54:55]
	v_exp_f32_e32 v152, v152
	v_exp_f32_e32 v153, v153
	v_exp_f32_e32 v154, v154
	v_exp_f32_e32 v155, v155
	v_pk_mul_f32 v[62:63], v[62:63], v[66:67]
	v_pk_mul_f32 v[64:65], v[64:65], v[68:69]
	v_pk_add_f32 v[152:153], v[152:153], 1.0 op_sel_hi:[1,0]
	v_pk_add_f32 v[154:155], v[154:155], 1.0 op_sel_hi:[1,0]
	v_rcp_f32_e32 v152, v152
	v_rcp_f32_e32 v153, v153
	v_rcp_f32_e32 v154, v154
	v_rcp_f32_e32 v155, v155
	v_pk_mul_f32 v[62:63], v[152:153], v[62:63]
	v_pk_mul_f32 v[64:65], v[154:155], v[64:65]
	v_cvt_pk_bf16_f32 v62, v62, v63
	v_cvt_pk_bf16_f32 v63, v64, v65
	v_pk_mul_f32 v[152:153], v[54:55], s[54:55]
	v_pk_mul_f32 v[154:155], v[56:57], s[54:55]
	v_exp_f32_e32 v152, v152
	v_exp_f32_e32 v153, v153
	v_exp_f32_e32 v154, v154
	v_exp_f32_e32 v155, v155
	v_pk_mul_f32 v[54:55], v[54:55], v[58:59]
	v_pk_mul_f32 v[56:57], v[56:57], v[60:61]
	v_pk_add_f32 v[152:153], v[152:153], 1.0 op_sel_hi:[1,0]
	v_pk_add_f32 v[154:155], v[154:155], 1.0 op_sel_hi:[1,0]
	v_rcp_f32_e32 v152, v152
	v_rcp_f32_e32 v153, v153
	v_rcp_f32_e32 v154, v154
	v_rcp_f32_e32 v155, v155
	v_pk_mul_f32 v[54:55], v[152:153], v[54:55]
	v_pk_mul_f32 v[56:57], v[154:155], v[56:57]
	v_cvt_pk_bf16_f32 v64, v54, v55
	v_cvt_pk_bf16_f32 v65, v56, v57
	global_store_dwordx4 v[150:151], v[62:65], off nt
	v_lshl_add_u64 v[150:151], v[150:151], 0, v[156:157]
	v_pk_mul_f32 v[152:153], v[46:47], s[54:55]
	v_pk_mul_f32 v[154:155], v[48:49], s[54:55]
	v_exp_f32_e32 v152, v152
	v_exp_f32_e32 v153, v153
	v_exp_f32_e32 v154, v154
	v_exp_f32_e32 v155, v155
	v_pk_mul_f32 v[46:47], v[46:47], v[50:51]
	v_pk_mul_f32 v[48:49], v[48:49], v[52:53]
	v_pk_add_f32 v[152:153], v[152:153], 1.0 op_sel_hi:[1,0]
	v_pk_add_f32 v[154:155], v[154:155], 1.0 op_sel_hi:[1,0]
	v_rcp_f32_e32 v152, v152
	v_rcp_f32_e32 v153, v153
	v_rcp_f32_e32 v154, v154
	v_rcp_f32_e32 v155, v155
	v_pk_mul_f32 v[46:47], v[152:153], v[46:47]
	v_pk_mul_f32 v[48:49], v[154:155], v[48:49]
	v_cvt_pk_bf16_f32 v46, v46, v47
	v_cvt_pk_bf16_f32 v47, v48, v49
	v_pk_mul_f32 v[152:153], v[38:39], s[54:55]
	v_pk_mul_f32 v[154:155], v[40:41], s[54:55]
	v_exp_f32_e32 v152, v152
	v_exp_f32_e32 v153, v153
	v_exp_f32_e32 v154, v154
	v_exp_f32_e32 v155, v155
	v_pk_mul_f32 v[38:39], v[38:39], v[42:43]
	v_pk_mul_f32 v[40:41], v[40:41], v[44:45]
	v_pk_add_f32 v[152:153], v[152:153], 1.0 op_sel_hi:[1,0]
	v_pk_add_f32 v[154:155], v[154:155], 1.0 op_sel_hi:[1,0]
	v_rcp_f32_e32 v152, v152
	v_rcp_f32_e32 v153, v153
	v_rcp_f32_e32 v154, v154
	v_rcp_f32_e32 v155, v155
	v_pk_mul_f32 v[38:39], v[152:153], v[38:39]
	v_pk_mul_f32 v[40:41], v[154:155], v[40:41]
	v_cvt_pk_bf16_f32 v48, v38, v39
	v_cvt_pk_bf16_f32 v49, v40, v41
	global_store_dwordx4 v[150:151], v[46:49], off nt
	v_lshl_add_u64 v[150:151], v[150:151], 0, v[156:157]
	v_pk_mul_f32 v[152:153], v[30:31], s[54:55]
	v_pk_mul_f32 v[154:155], v[32:33], s[54:55]
	v_exp_f32_e32 v152, v152
	v_exp_f32_e32 v153, v153
	v_exp_f32_e32 v154, v154
	v_exp_f32_e32 v155, v155
	v_pk_mul_f32 v[30:31], v[30:31], v[34:35]
	v_pk_mul_f32 v[32:33], v[32:33], v[36:37]
	v_pk_add_f32 v[152:153], v[152:153], 1.0 op_sel_hi:[1,0]
	v_pk_add_f32 v[154:155], v[154:155], 1.0 op_sel_hi:[1,0]
	v_rcp_f32_e32 v152, v152
	v_rcp_f32_e32 v153, v153
	v_rcp_f32_e32 v154, v154
	v_rcp_f32_e32 v155, v155
	v_pk_mul_f32 v[30:31], v[152:153], v[30:31]
	v_pk_mul_f32 v[32:33], v[154:155], v[32:33]
	v_cvt_pk_bf16_f32 v30, v30, v31
	v_cvt_pk_bf16_f32 v31, v32, v33
	v_pk_mul_f32 v[152:153], v[22:23], s[54:55]
	v_pk_mul_f32 v[154:155], v[24:25], s[54:55]
	v_exp_f32_e32 v152, v152
	v_exp_f32_e32 v153, v153
	v_exp_f32_e32 v154, v154
	v_exp_f32_e32 v155, v155
	v_pk_mul_f32 v[22:23], v[22:23], v[26:27]
	v_pk_mul_f32 v[24:25], v[24:25], v[28:29]
	v_pk_add_f32 v[152:153], v[152:153], 1.0 op_sel_hi:[1,0]
	v_pk_add_f32 v[154:155], v[154:155], 1.0 op_sel_hi:[1,0]
	v_rcp_f32_e32 v152, v152
	v_rcp_f32_e32 v153, v153
	v_rcp_f32_e32 v154, v154
	v_rcp_f32_e32 v155, v155
	v_pk_mul_f32 v[22:23], v[152:153], v[22:23]
	v_pk_mul_f32 v[24:25], v[154:155], v[24:25]
	v_cvt_pk_bf16_f32 v32, v22, v23
	v_cvt_pk_bf16_f32 v33, v24, v25
	global_store_dwordx4 v[150:151], v[30:33], off nt
	v_lshl_add_u64 v[150:151], v[150:151], 0, v[156:157]
	v_pk_mul_f32 v[152:153], v[14:15], s[54:55]
	v_pk_mul_f32 v[154:155], v[16:17], s[54:55]
	v_exp_f32_e32 v152, v152
	v_exp_f32_e32 v153, v153
	v_exp_f32_e32 v154, v154
	v_exp_f32_e32 v155, v155
	v_pk_mul_f32 v[14:15], v[14:15], v[18:19]
	v_pk_mul_f32 v[16:17], v[16:17], v[20:21]
	v_pk_add_f32 v[152:153], v[152:153], 1.0 op_sel_hi:[1,0]
	v_pk_add_f32 v[154:155], v[154:155], 1.0 op_sel_hi:[1,0]
	v_rcp_f32_e32 v152, v152
	v_rcp_f32_e32 v153, v153
	v_rcp_f32_e32 v154, v154
	v_rcp_f32_e32 v155, v155
	v_pk_mul_f32 v[14:15], v[152:153], v[14:15]
	v_pk_mul_f32 v[16:17], v[154:155], v[16:17]
	v_cvt_pk_bf16_f32 v14, v14, v15
	v_cvt_pk_bf16_f32 v15, v16, v17
	v_pk_mul_f32 v[152:153], v[10:11], s[54:55]
	v_pk_mul_f32 v[154:155], v[12:13], s[54:55]
	v_exp_f32_e32 v152, v152
	v_exp_f32_e32 v153, v153
	v_exp_f32_e32 v154, v154
	v_exp_f32_e32 v155, v155
	v_pk_mul_f32 v[10:11], v[10:11], v[6:7]
	v_pk_mul_f32 v[12:13], v[12:13], v[8:9]
	v_pk_add_f32 v[152:153], v[152:153], 1.0 op_sel_hi:[1,0]
	v_pk_add_f32 v[154:155], v[154:155], 1.0 op_sel_hi:[1,0]
	v_rcp_f32_e32 v152, v152
	v_rcp_f32_e32 v153, v153
	v_rcp_f32_e32 v154, v154
	v_rcp_f32_e32 v155, v155
	v_pk_mul_f32 v[10:11], v[152:153], v[10:11]
	v_pk_mul_f32 v[12:13], v[154:155], v[12:13]
	v_cvt_pk_bf16_f32 v16, v10, v11
	v_cvt_pk_bf16_f32 v17, v12, v13
	global_store_dwordx4 v[150:151], v[14:17], off nt
	s_mov_b64 s[82:83], -1
	s_andn2_b64 vcc, exec, s[4:5]
	s_cbranch_vccnz .LBB0_184
	s_andn2_b64 vcc, exec, s[70:71]
	s_cbranch_vccnz .LBB0_183
	s_barrier
	s_branch .LBB0_183

; #define PG8_GAS __attribute__((address_space(1)))
; #define PG8_BAR __builtin_amdgcn_s_barrier()
; template <class T> __device__ __forceinline__ GAS T* gp(T* p) { return (GAS T*)p; }
;     __device__ __forceinline__ void operator()(const f32x4 (&acc)[2][2][4][2], const Unit& u, int wr, int wc, int fr, int fq) const {
;         const int b = (u.pm * BM) >> 13;
;         const float* gp = mod + b * 9216 + step * 3072 + 2048; const float coef = step == 1 ? 1.0f : 0.5f;
;         const float* basef = step == 0 ? xin : (const float*)nullptr; const bf16_t* baseb = xs; bf16_t* out = xs;
;         const int col0 = u.pn * BM + wc * 32 + 8 * fq;
;         f32x4 gv[2][2];
; #pragma unroll
;         for (int bj = 0; bj < 2; ++bj)
; #pragma unroll
;             for (int n = 0; n < 2; ++n) gv[bj][n] = (*(const PG8_GAS f32x4*)(gp + col0 + bj * HALF + 4 * n) + 1.0f) * coef;
; #pragma unroll
;         for (int ai = 0; ai < 2; ++ai)
; #pragma unroll
;             for (int m = 0; m < 4; ++m) {
;                 const size_t off = (size_t)(u.pm * BM + ai * HALF + wr * 64 + m * 16 + fr) * 1024 + col0;
; #pragma unroll
;                 for (int bj = 0; bj < 2; ++bj) {
;                     f32x4 b0, b1;
;                     if (basef) { b0 = __builtin_nontemporal_load((const PG8_GAS f32x4*)(basef + off + bj * HALF)); b1 = __builtin_nontemporal_load((const PG8_GAS f32x4*)(basef + off + bj * HALF + 4)); }
;                     else { const u32x4 w = __builtin_nontemporal_load((const PG8_GAS u32x4*)(baseb + off + bj * HALF));
;                         b0 = (f32x4){__uint_as_float(w.x << 16), __uint_as_float(w.x & 0xffff0000u), __uint_as_float(w.y << 16), __uint_as_float(w.y & 0xffff0000u)};
;                         b1 = (f32x4){__uint_as_float(w.z << 16), __uint_as_float(w.z & 0xffff0000u), __uint_as_float(w.w << 16), __uint_as_float(w.w & 0xffff0000u)}; }
;                     const f32x4 o0 = b0 + gv[bj][0] * acc[ai][bj][m][0], o1 = b1 + gv[bj][1] * acc[ai][bj][m][1];
; template <class Epi, class Sched, bool ALIGN_EPI = false, bool SP2 = false>
; __device__ __forceinline__ void gemm_phase(PG8_LAS unsigned char* lds, const Gemm g, const Sched& S, const Epi& E, const int tid) {
;     ...
;         if constexpr (ALIGN_EPI) { if (wr == 0) PG8_BAR; }
.LBB0_626:
.LBB0_628:
	s_lshr_b32 s4, s25, 5
	s_mulk_i32 s4, 0x2400
	s_ashr_i32 s5, s4, 31
	s_lshl_b64 s[4:5], s[4:5], 2
	s_add_u32 s4, s38, s4
	v_lshl_or_b32 v2, s40, 8, v178
	s_addc_u32 s5, s18, s5
	v_ashrrev_i32_e32 v3, 31, v2
	v_lshl_add_u64 v[134:135], v[2:3], 2, s[4:5]
	s_mov_b64 s[4:5], 0x2000
	v_lshl_add_u64 v[138:139], v[134:135], 0, s[4:5]
	v_add_co_u32_e32 v134, vcc, s47, v134
	v_add_u32_e32 v170, s42, v176
	s_nop 0
	v_addc_co_u32_e32 v135, vcc, 0, v135, vcc
	global_load_dwordx4 v[146:149], v[134:135], off
	s_nop 0
	global_load_dwordx4 v[134:137], v[138:139], off offset:528
	global_load_dwordx4 v[142:145], v[138:139], off offset:16
	s_nop 0
	global_load_dwordx4 v[138:141], v[138:139], off offset:512
	v_ashrrev_i32_e32 v171, 31, v170
	v_lshlrev_b64 v[150:151], 10, v[170:171]
	v_lshl_add_u64 v[150:151], v[150:151], 0, v[2:3]
	v_lshl_add_u64 v[2:3], v[150:151], 1, s[56:57]
	v_lshl_add_u64 v[174:175], v[150:151], 2, s[64:65]
	v_mov_b64_e32 v[182:183], v[2:3]
	s_andn2_b64 vcc, exec, s[66:67]
	s_cbranch_vccnz .Lres_epi_bf16
	s_mov_b32 s4, 0x10000
	s_mov_b32 s5, 0
	s_mov_b32 vcc_lo, 0x50000
	s_mov_b32 vcc_hi, 0
	global_load_dwordx4 v[150:153], v[174:175], off nt
	global_load_dwordx4 v[154:157], v[174:175], off offset:16 nt
	global_load_dwordx4 v[170:173], v[174:175], off offset:512 nt
	global_load_dwordx4 v[184:187], v[174:175], off offset:528 nt
	v_lshl_add_u64 v[174:175], v[174:175], 0, s[4:5]
	global_load_dwordx4 v[188:191], v[174:175], off nt
	global_load_dwordx4 v[192:195], v[174:175], off offset:16 nt
	global_load_dwordx4 v[208:211], v[174:175], off offset:512 nt
	global_load_dwordx4 v[226:229], v[174:175], off offset:528 nt
	v_lshl_add_u64 v[174:175], v[174:175], 0, s[4:5]
	global_load_dwordx4 v[230:233], v[174:175], off nt
	global_load_dwordx4 v[234:237], v[174:175], off offset:16 nt
	global_load_dwordx4 v[238:241], v[174:175], off offset:512 nt
	global_load_dwordx4 v[242:245], v[174:175], off offset:528 nt
	v_lshl_add_u64 v[174:175], v[174:175], 0, s[4:5]
	global_load_dwordx4 v[246:249], v[174:175], off nt
	global_load_dwordx4 v[250:253], v[174:175], off offset:16 nt
	s_cmp_eq_u64 s[78:79], 0
	s_cbranch_scc1 .Lres_nb_f32
	s_barrier
.Lres_nb_f32:
	s_waitcnt vmcnt(12)
	v_pk_add_f32 v[148:149], v[148:149], 1.0 op_sel_hi:[1,0]
	v_pk_add_f32 v[180:181], v[146:147], 1.0 op_sel_hi:[1,0]
	v_pk_mul_f32 v[146:147], s[60:61], v[148:149]
	v_pk_mul_f32 v[148:149], s[10:11], v[180:181]
	v_pk_add_f32 v[180:181], v[142:143], 1.0 op_sel_hi:[1,0]
	v_pk_add_f32 v[142:143], v[144:145], 1.0 op_sel_hi:[1,0]
	v_pk_mul_f32 v[144:145], s[10:11], v[180:181]
	v_pk_mul_f32 v[142:143], s[60:61], v[142:143]
	v_pk_add_f32 v[140:141], v[140:141], 1.0 op_sel_hi:[1,0]
	v_pk_add_f32 v[180:181], v[138:139], 1.0 op_sel_hi:[1,0]
	v_pk_mul_f32 v[138:139], s[60:61], v[140:141]
	v_pk_mul_f32 v[140:141], s[10:11], v[180:181]
	v_pk_add_f32 v[180:181], v[134:135], 1.0 op_sel_hi:[1,0]
	v_pk_add_f32 v[134:135], v[136:137], 1.0 op_sel_hi:[1,0]
	v_pk_mul_f32 v[136:137], s[10:11], v[180:181]
	v_pk_mul_f32 v[134:135], s[60:61], v[134:135]
	v_pk_fma_f32 v[130:131], v[130:131], v[148:149], v[150:151]
	v_pk_fma_f32 v[132:133], v[132:133], v[146:147], v[152:153]
	v_pk_fma_f32 v[126:127], v[126:127], v[144:145], v[154:155]
	v_pk_fma_f32 v[128:129], v[128:129], v[142:143], v[156:157]
	v_cvt_pk_bf16_f32 v130, v130, v131
	v_cvt_pk_bf16_f32 v131, v132, v133
	v_cvt_pk_bf16_f32 v132, v126, v127
	v_cvt_pk_bf16_f32 v133, v128, v129
	global_load_dwordx4 v[150:153], v[174:175], off offset:512 nt
	global_load_dwordx4 v[154:157], v[174:175], off offset:528 nt
	v_lshl_add_u64 v[174:175], v[174:175], 0, vcc
	s_waitcnt vmcnt(12)
	v_pk_fma_f32 v[122:123], v[122:123], v[140:141], v[170:171]
	v_pk_fma_f32 v[124:125], v[124:125], v[138:139], v[172:173]
	v_pk_fma_f32 v[118:119], v[118:119], v[136:137], v[184:185]
	v_pk_fma_f32 v[120:121], v[120:121], v[134:135], v[186:187]
	v_cvt_pk_bf16_f32 v122, v122, v123
	v_cvt_pk_bf16_f32 v123, v124, v125
	v_cvt_pk_bf16_f32 v124, v118, v119
	v_cvt_pk_bf16_f32 v125, v120, v121
	global_load_dwordx4 v[126:129], v[174:175], off nt
	global_load_dwordx4 v[170:173], v[174:175], off offset:16 nt
	global_load_dwordx4 v[184:187], v[174:175], off offset:512 nt
	global_load_dwordx4 v[118:121], v[174:175], off offset:528 nt
	v_lshl_add_u64 v[174:175], v[174:175], 0, s[4:5]
	s_waitcnt vmcnt(14)
	v_pk_fma_f32 v[114:115], v[114:115], v[148:149], v[188:189]
	v_pk_fma_f32 v[116:117], v[116:117], v[146:147], v[190:191]
	v_pk_fma_f32 v[110:111], v[110:111], v[144:145], v[192:193]
	v_pk_fma_f32 v[112:113], v[112:113], v[142:143], v[194:195]
	v_cvt_pk_bf16_f32 v114, v114, v115
	v_cvt_pk_bf16_f32 v115, v116, v117
	v_cvt_pk_bf16_f32 v116, v110, v111
	v_cvt_pk_bf16_f32 v117, v112, v113
	global_load_dwordx4 v[188:191], v[174:175], off nt
	global_load_dwordx4 v[192:195], v[174:175], off offset:16 nt
	s_waitcnt vmcnt(14)
	v_pk_fma_f32 v[106:107], v[106:107], v[140:141], v[208:209]
	v_pk_fma_f32 v[108:109], v[108:109], v[138:139], v[210:211]
	v_pk_fma_f32 v[102:103], v[102:103], v[136:137], v[226:227]
	v_pk_fma_f32 v[104:105], v[104:105], v[134:135], v[228:229]
	v_cvt_pk_bf16_f32 v106, v106, v107
	v_cvt_pk_bf16_f32 v107, v108, v109
	v_cvt_pk_bf16_f32 v108, v102, v103
	v_cvt_pk_bf16_f32 v109, v104, v105
	global_load_dwordx4 v[110:113], v[174:175], off offset:512 nt
	global_load_dwordx4 v[208:211], v[174:175], off offset:528 nt
	v_lshl_add_u64 v[174:175], v[174:175], 0, s[4:5]
	global_load_dwordx4 v[226:229], v[174:175], off nt
	global_load_dwordx4 v[102:105], v[174:175], off offset:16 nt
	s_waitcnt vmcnt(16)
; #define PG8_GAS __attribute__((address_space(1)))
; __device__ __forceinline__ unsigned cvtpk(float lo, float hi) { f32x2 v = {lo, hi}; bf16x2_t b = __builtin_convertvector(v, bf16x2_t); return __builtin_bit_cast(unsigned, b); }
;     __device__ __forceinline__ void operator()(const f32x4 (&acc)[2][2][4][2], const Unit& u, int wr, int wc, int fr, int fq) const {
;     ...
;                 for (int bj = 0; bj < 2; ++bj) {
;                     f32x4 b0, b1;
;                     if (basef) { b0 = __builtin_nontemporal_load((const PG8_GAS f32x4*)(basef + off + bj * HALF)); b1 = __builtin_nontemporal_load((const PG8_GAS f32x4*)(basef + off + bj * HALF + 4)); }
;                     else { const u32x4 w = __builtin_nontemporal_load((const PG8_GAS u32x4*)(baseb + off + bj * HALF));
;                         b0 = (f32x4){__uint_as_float(w.x << 16), __uint_as_float(w.x & 0xffff0000u), __uint_as_float(w.y << 16), __uint_as_float(w.y & 0xffff0000u)};
;                         b1 = (f32x4){__uint_as_float(w.z << 16), __uint_as_float(w.z & 0xffff0000u), __uint_as_float(w.w << 16), __uint_as_float(w.w & 0xffff0000u)}; }
;                     const f32x4 o0 = b0 + gv[bj][0] * acc[ai][bj][m][0], o1 = b1 + gv[bj][1] * acc[ai][bj][m][1];
;                     u32x4 w; w.x = cvtpk(o0[0], o0[1]); w.y = cvtpk(o0[2], o0[3]); w.z = cvtpk(o1[0], o1[1]); w.w = cvtpk(o1[2], o1[3]);
;                     __builtin_nontemporal_store(w, (PG8_GAS u32x4*)(out + off + bj * HALF));
	v_pk_fma_f32 v[98:99], v[98:99], v[148:149], v[230:231]
	v_pk_fma_f32 v[100:101], v[100:101], v[146:147], v[232:233]
	v_pk_fma_f32 v[94:95], v[94:95], v[144:145], v[234:235]
	v_pk_fma_f32 v[96:97], v[96:97], v[142:143], v[236:237]
	v_cvt_pk_bf16_f32 v98, v98, v99
	v_cvt_pk_bf16_f32 v99, v100, v101
	v_cvt_pk_bf16_f32 v100, v94, v95
	v_cvt_pk_bf16_f32 v101, v96, v97
	global_load_dwordx4 v[230:233], v[174:175], off offset:512 nt
	global_load_dwordx4 v[234:237], v[174:175], off offset:528 nt
	v_lshl_add_u64 v[174:175], v[174:175], 0, s[4:5]
	s_waitcnt vmcnt(16)
	v_pk_fma_f32 v[90:91], v[90:91], v[140:141], v[238:239]
	v_pk_fma_f32 v[92:93], v[92:93], v[138:139], v[240:241]
	v_pk_fma_f32 v[86:87], v[86:87], v[136:137], v[242:243]
	v_pk_fma_f32 v[88:89], v[88:89], v[134:135], v[244:245]
	v_cvt_pk_bf16_f32 v90, v90, v91
	v_cvt_pk_bf16_f32 v91, v92, v93
	v_cvt_pk_bf16_f32 v92, v86, v87
	v_cvt_pk_bf16_f32 v93, v88, v89
	global_load_dwordx4 v[94:97], v[174:175], off nt
	global_load_dwordx4 v[238:241], v[174:175], off offset:16 nt
	global_load_dwordx4 v[242:245], v[174:175], off offset:512 nt
	global_load_dwordx4 v[86:89], v[174:175], off offset:528 nt
	s_mov_b32 s4, 0x8000
	s_mov_b32 vcc_lo, 0x28000
	global_store_dwordx4 v[2:3], v[130:133], off
	global_store_dwordx4 v[2:3], v[122:125], off offset:256
	v_lshl_add_u64 v[2:3], v[2:3], 0, s[4:5]
	global_store_dwordx4 v[2:3], v[114:117], off
	global_store_dwordx4 v[2:3], v[106:109], off offset:256
	v_lshl_add_u64 v[2:3], v[2:3], 0, s[4:5]
	global_store_dwordx4 v[2:3], v[98:101], off
	global_store_dwordx4 v[2:3], v[90:93], off offset:256
	v_lshl_add_u64 v[2:3], v[2:3], 0, s[4:5]
	s_waitcnt vmcnt(24)
	v_pk_fma_f32 v[82:83], v[82:83], v[148:149], v[246:247]
	v_pk_fma_f32 v[84:85], v[84:85], v[146:147], v[248:249]
	v_pk_fma_f32 v[78:79], v[78:79], v[144:145], v[250:251]
	v_pk_fma_f32 v[80:81], v[80:81], v[142:143], v[252:253]
	v_cvt_pk_bf16_f32 v82, v82, v83
	v_cvt_pk_bf16_f32 v83, v84, v85
	v_cvt_pk_bf16_f32 v84, v78, v79
	v_cvt_pk_bf16_f32 v85, v80, v81
	global_store_dwordx4 v[2:3], v[82:85], off
	s_waitcnt vmcnt(23)
	v_pk_fma_f32 v[74:75], v[74:75], v[140:141], v[150:151]
	v_pk_fma_f32 v[76:77], v[76:77], v[138:139], v[152:153]
	v_pk_fma_f32 v[70:71], v[70:71], v[136:137], v[154:155]
	v_pk_fma_f32 v[72:73], v[72:73], v[134:135], v[156:157]
	v_cvt_pk_bf16_f32 v74, v74, v75
	v_cvt_pk_bf16_f32 v75, v76, v77
	v_cvt_pk_bf16_f32 v76, v70, v71
	v_cvt_pk_bf16_f32 v77, v72, v73
	global_store_dwordx4 v[2:3], v[74:77], off offset:256
	v_lshl_add_u64 v[2:3], v[2:3], 0, vcc
	s_waitcnt vmcnt(22)
	v_pk_fma_f32 v[66:67], v[66:67], v[148:149], v[126:127]
	v_pk_fma_f32 v[68:69], v[68:69], v[146:147], v[128:129]
	v_pk_fma_f32 v[62:63], v[62:63], v[144:145], v[170:171]
	v_pk_fma_f32 v[64:65], v[64:65], v[142:143], v[172:173]
	v_cvt_pk_bf16_f32 v66, v66, v67
	v_cvt_pk_bf16_f32 v67, v68, v69
	v_cvt_pk_bf16_f32 v68, v62, v63
	v_cvt_pk_bf16_f32 v69, v64, v65
	global_store_dwordx4 v[2:3], v[66:69], off
	s_waitcnt vmcnt(21)
	v_pk_fma_f32 v[58:59], v[58:59], v[140:141], v[184:185]
	v_pk_fma_f32 v[60:61], v[60:61], v[138:139], v[186:187]
	v_pk_fma_f32 v[54:55], v[54:55], v[136:137], v[118:119]
	v_pk_fma_f32 v[56:57], v[56:57], v[134:135], v[120:121]
	v_cvt_pk_bf16_f32 v58, v58, v59
	v_cvt_pk_bf16_f32 v59, v60, v61
	v_cvt_pk_bf16_f32 v60, v54, v55
	v_cvt_pk_bf16_f32 v61, v56, v57
	global_store_dwordx4 v[2:3], v[58:61], off offset:256
	v_lshl_add_u64 v[2:3], v[2:3], 0, s[4:5]
	s_waitcnt vmcnt(20)
	v_pk_fma_f32 v[50:51], v[50:51], v[148:149], v[188:189]
	v_pk_fma_f32 v[52:53], v[52:53], v[146:147], v[190:191]
	v_pk_fma_f32 v[46:47], v[46:47], v[144:145], v[192:193]
	v_pk_fma_f32 v[48:49], v[48:49], v[142:143], v[194:195]
	v_cvt_pk_bf16_f32 v50, v50, v51
	v_cvt_pk_bf16_f32 v51, v52, v53
	v_cvt_pk_bf16_f32 v52, v46, v47
	v_cvt_pk_bf16_f32 v53, v48, v49
	global_store_dwordx4 v[2:3], v[50:53], off
	s_waitcnt vmcnt(19)
	v_pk_fma_f32 v[42:43], v[42:43], v[140:141], v[110:111]
	v_pk_fma_f32 v[44:45], v[44:45], v[138:139], v[112:113]
	v_pk_fma_f32 v[38:39], v[38:39], v[136:137], v[208:209]
	v_pk_fma_f32 v[40:41], v[40:41], v[134:135], v[210:211]
	v_cvt_pk_bf16_f32 v42, v42, v43
	v_cvt_pk_bf16_f32 v43, v44, v45
	v_cvt_pk_bf16_f32 v44, v38, v39
	v_cvt_pk_bf16_f32 v45, v40, v41
	global_store_dwordx4 v[2:3], v[42:45], off offset:256
	v_lshl_add_u64 v[2:3], v[2:3], 0, s[4:5]
	s_waitcnt vmcnt(18)
	v_pk_fma_f32 v[34:35], v[34:35], v[148:149], v[226:227]
	v_pk_fma_f32 v[36:37], v[36:37], v[146:147], v[228:229]
	v_pk_fma_f32 v[30:31], v[30:31], v[144:145], v[102:103]
	v_pk_fma_f32 v[32:33], v[32:33], v[142:143], v[104:105]
	v_cvt_pk_bf16_f32 v34, v34, v35
	v_cvt_pk_bf16_f32 v35, v36, v37
	v_cvt_pk_bf16_f32 v36, v30, v31
	v_cvt_pk_bf16_f32 v37, v32, v33
	global_store_dwordx4 v[2:3], v[34:37], off
	s_waitcnt vmcnt(17)
	v_pk_fma_f32 v[26:27], v[26:27], v[140:141], v[230:231]
	v_pk_fma_f32 v[28:29], v[28:29], v[138:139], v[232:233]
	v_pk_fma_f32 v[22:23], v[22:23], v[136:137], v[234:235]
	v_pk_fma_f32 v[24:25], v[24:25], v[134:135], v[236:237]
	v_cvt_pk_bf16_f32 v26, v26, v27
	v_cvt_pk_bf16_f32 v27, v28, v29
	v_cvt_pk_bf16_f32 v28, v22, v23
	v_cvt_pk_bf16_f32 v29, v24, v25
	global_store_dwordx4 v[2:3], v[26:29], off offset:256
	v_lshl_add_u64 v[2:3], v[2:3], 0, s[4:5]
	s_waitcnt vmcnt(16)
	v_pk_fma_f32 v[18:19], v[18:19], v[148:149], v[94:95]
	v_pk_fma_f32 v[20:21], v[20:21], v[146:147], v[96:97]
	v_pk_fma_f32 v[14:15], v[14:15], v[144:145], v[238:239]
	v_pk_fma_f32 v[16:17], v[16:17], v[142:143], v[240:241]
	v_cvt_pk_bf16_f32 v18, v18, v19
	v_cvt_pk_bf16_f32 v19, v20, v21
	v_cvt_pk_bf16_f32 v20, v14, v15
	v_cvt_pk_bf16_f32 v21, v16, v17
	global_store_dwordx4 v[2:3], v[18:21], off
	s_waitcnt vmcnt(15)
	v_pk_fma_f32 v[10:11], v[10:11], v[140:141], v[242:243]
	v_pk_fma_f32 v[12:13], v[12:13], v[138:139], v[244:245]
	v_pk_fma_f32 v[6:7], v[6:7], v[136:137], v[86:87]
	v_pk_fma_f32 v[8:9], v[8:9], v[134:135], v[88:89]
	v_cvt_pk_bf16_f32 v10, v10, v11
	v_cvt_pk_bf16_f32 v11, v12, v13
	v_cvt_pk_bf16_f32 v12, v6, v7
	v_cvt_pk_bf16_f32 v13, v8, v9
	s_and_b64 vcc, exec, s[6:7]
	s_mov_b64 s[4:5], -1
	global_store_dwordx4 v[2:3], v[10:13], off offset:256
	s_branch .Lres_epi_tail
; #define PG8_GAS __attribute__((address_space(1)))
; __device__ __forceinline__ unsigned cvtpk(float lo, float hi) { f32x2 v = {lo, hi}; bf16x2_t b = __builtin_convertvector(v, bf16x2_t); return __builtin_bit_cast(unsigned, b); }
;     __device__ __forceinline__ void operator()(const f32x4 (&acc)[2][2][4][2], const Unit& u, int wr, int wc, int fr, int fq) const {
;     ...
; #pragma unroll
;                 for (int bj = 0; bj < 2; ++bj) {
;                     f32x4 b0, b1;
;                     if (basef) { b0 = __builtin_nontemporal_load((const PG8_GAS f32x4*)(basef + off + bj * HALF)); b1 = __builtin_nontemporal_load((const PG8_GAS f32x4*)(basef + off + bj * HALF + 4)); }
;                     else { const u32x4 w = __builtin_nontemporal_load((const PG8_GAS u32x4*)(baseb + off + bj * HALF));
;                         b0 = (f32x4){__uint_as_float(w.x << 16), __uint_as_float(w.x & 0xffff0000u), __uint_as_float(w.y << 16), __uint_as_float(w.y & 0xffff0000u)};
;                         b1 = (f32x4){__uint_as_float(w.z << 16), __uint_as_float(w.z & 0xffff0000u), __uint_as_float(w.w << 16), __uint_as_float(w.w & 0xffff0000u)}; }
;                     const f32x4 o0 = b0 + gv[bj][0] * acc[ai][bj][m][0], o1 = b1 + gv[bj][1] * acc[ai][bj][m][1];
;                     u32x4 w; w.x = cvtpk(o0[0], o0[1]); w.y = cvtpk(o0[2], o0[3]); w.z = cvtpk(o1[0], o1[1]); w.w = cvtpk(o1[2], o1[3]);
;                     __builtin_nontemporal_store(w, (PG8_GAS u32x4*)(out + off + bj * HALF));
.Lres_epi_bf16:
	s_mov_b32 s4, 0x8000
	s_mov_b32 s5, 0
	s_mov_b32 vcc_lo, 0x28000
	s_mov_b32 vcc_hi, 0
	global_load_dwordx4 v[150:153], v[182:183], off nt
	global_load_dwordx4 v[154:157], v[182:183], off offset:256 nt
	v_lshl_add_u64 v[182:183], v[182:183], 0, s[4:5]
	global_load_dwordx4 v[170:173], v[182:183], off nt
	global_load_dwordx4 v[184:187], v[182:183], off offset:256 nt
	v_lshl_add_u64 v[182:183], v[182:183], 0, s[4:5]
	global_load_dwordx4 v[188:191], v[182:183], off nt
	global_load_dwordx4 v[192:195], v[182:183], off offset:256 nt
	v_lshl_add_u64 v[182:183], v[182:183], 0, s[4:5]
	global_load_dwordx4 v[208:211], v[182:183], off nt
	global_load_dwordx4 v[226:229], v[182:183], off offset:256 nt
	v_lshl_add_u64 v[182:183], v[182:183], 0, vcc
	global_load_dwordx4 v[230:233], v[182:183], off nt
	global_load_dwordx4 v[234:237], v[182:183], off offset:256 nt
	v_lshl_add_u64 v[182:183], v[182:183], 0, s[4:5]
	global_load_dwordx4 v[238:241], v[182:183], off nt
	global_load_dwordx4 v[242:245], v[182:183], off offset:256 nt
	v_lshl_add_u64 v[182:183], v[182:183], 0, s[4:5]
	global_load_dwordx4 v[246:249], v[182:183], off nt
	global_load_dwordx4 v[250:253], v[182:183], off offset:256 nt
	v_lshl_add_u64 v[182:183], v[182:183], 0, s[4:5]
	s_cmp_eq_u64 s[78:79], 0
	s_cbranch_scc1 .Lres_nb_bf16
	s_barrier
.Lres_nb_bf16:
	s_waitcnt vmcnt(13)
	v_pk_add_f32 v[148:149], v[148:149], 1.0 op_sel_hi:[1,0]
	v_pk_add_f32 v[180:181], v[146:147], 1.0 op_sel_hi:[1,0]
	v_pk_mul_f32 v[146:147], s[60:61], v[148:149]
	v_pk_mul_f32 v[148:149], s[10:11], v[180:181]
	v_pk_add_f32 v[180:181], v[142:143], 1.0 op_sel_hi:[1,0]
	v_pk_add_f32 v[142:143], v[144:145], 1.0 op_sel_hi:[1,0]
	v_pk_mul_f32 v[144:145], s[10:11], v[180:181]
	v_pk_mul_f32 v[142:143], s[60:61], v[142:143]
	v_pk_add_f32 v[140:141], v[140:141], 1.0 op_sel_hi:[1,0]
	v_pk_add_f32 v[180:181], v[138:139], 1.0 op_sel_hi:[1,0]
	v_pk_mul_f32 v[138:139], s[60:61], v[140:141]
	v_pk_mul_f32 v[140:141], s[10:11], v[180:181]
	v_pk_add_f32 v[180:181], v[134:135], 1.0 op_sel_hi:[1,0]
	v_pk_add_f32 v[134:135], v[136:137], 1.0 op_sel_hi:[1,0]
	v_pk_mul_f32 v[136:137], s[10:11], v[180:181]
	v_pk_mul_f32 v[134:135], s[60:61], v[134:135]
	v_lshlrev_b32_e32 v180, 16, v150
	v_and_b32_e32 v181, 0xffff0000, v150
	v_pk_fma_f32 v[130:131], v[130:131], v[148:149], v[180:181]
	v_lshlrev_b32_e32 v150, 16, v151
	v_and_b32_e32 v151, 0xffff0000, v151
	v_pk_fma_f32 v[132:133], v[132:133], v[146:147], v[150:151]
	v_lshlrev_b32_e32 v180, 16, v152
	v_and_b32_e32 v181, 0xffff0000, v152
	v_pk_fma_f32 v[126:127], v[126:127], v[144:145], v[180:181]
	v_lshlrev_b32_e32 v152, 16, v153
	v_and_b32_e32 v153, 0xffff0000, v153
	v_pk_fma_f32 v[128:129], v[128:129], v[142:143], v[152:153]
	v_cvt_pk_bf16_f32 v130, v130, v131
	v_cvt_pk_bf16_f32 v131, v132, v133
	v_cvt_pk_bf16_f32 v132, v126, v127
	v_cvt_pk_bf16_f32 v133, v128, v129
	global_load_dwordx4 v[150:153], v[182:183], off nt
	global_load_dwordx4 v[126:129], v[182:183], off offset:256 nt
	global_store_dwordx4 v[2:3], v[130:133], off
	s_waitcnt vmcnt(15)
	v_lshlrev_b32_e32 v180, 16, v154
	v_and_b32_e32 v181, 0xffff0000, v154
	v_pk_fma_f32 v[122:123], v[122:123], v[140:141], v[180:181]
	v_lshlrev_b32_e32 v154, 16, v155
	v_and_b32_e32 v155, 0xffff0000, v155
	v_pk_fma_f32 v[124:125], v[124:125], v[138:139], v[154:155]
	v_lshlrev_b32_e32 v180, 16, v156
	v_and_b32_e32 v181, 0xffff0000, v156
	v_pk_fma_f32 v[118:119], v[118:119], v[136:137], v[180:181]
	v_lshlrev_b32_e32 v156, 16, v157
	v_and_b32_e32 v157, 0xffff0000, v157
	v_pk_fma_f32 v[120:121], v[120:121], v[134:135], v[156:157]
	v_cvt_pk_bf16_f32 v122, v122, v123
	v_cvt_pk_bf16_f32 v123, v124, v125
	v_cvt_pk_bf16_f32 v124, v118, v119
	v_cvt_pk_bf16_f32 v125, v120, v121
	global_store_dwordx4 v[2:3], v[122:125], off offset:256
	v_lshl_add_u64 v[2:3], v[2:3], 0, s[4:5]
	s_waitcnt vmcnt(15)
	v_lshlrev_b32_e32 v180, 16, v170
	v_and_b32_e32 v181, 0xffff0000, v170
	v_pk_fma_f32 v[114:115], v[114:115], v[148:149], v[180:181]
	v_lshlrev_b32_e32 v170, 16, v171
	v_and_b32_e32 v171, 0xffff0000, v171
	v_pk_fma_f32 v[116:117], v[116:117], v[146:147], v[170:171]
	v_lshlrev_b32_e32 v180, 16, v172
	v_and_b32_e32 v181, 0xffff0000, v172
	v_pk_fma_f32 v[110:111], v[110:111], v[144:145], v[180:181]
	v_lshlrev_b32_e32 v172, 16, v173
	v_and_b32_e32 v173, 0xffff0000, v173
	v_pk_fma_f32 v[112:113], v[112:113], v[142:143], v[172:173]
	v_cvt_pk_bf16_f32 v114, v114, v115
	v_cvt_pk_bf16_f32 v115, v116, v117
	v_cvt_pk_bf16_f32 v116, v110, v111
	v_cvt_pk_bf16_f32 v117, v112, v113
	global_store_dwordx4 v[2:3], v[114:117], off
	s_waitcnt vmcnt(15)
	v_lshlrev_b32_e32 v180, 16, v184
	v_and_b32_e32 v181, 0xffff0000, v184
	v_pk_fma_f32 v[106:107], v[106:107], v[140:141], v[180:181]
	v_lshlrev_b32_e32 v184, 16, v185
	v_and_b32_e32 v185, 0xffff0000, v185
	v_pk_fma_f32 v[108:109], v[108:109], v[138:139], v[184:185]
	v_lshlrev_b32_e32 v180, 16, v186
	v_and_b32_e32 v181, 0xffff0000, v186
	v_pk_fma_f32 v[102:103], v[102:103], v[136:137], v[180:181]
	v_lshlrev_b32_e32 v186, 16, v187
	v_and_b32_e32 v187, 0xffff0000, v187
	v_pk_fma_f32 v[104:105], v[104:105], v[134:135], v[186:187]
	v_cvt_pk_bf16_f32 v106, v106, v107
	v_cvt_pk_bf16_f32 v107, v108, v109
	v_cvt_pk_bf16_f32 v108, v102, v103
	v_cvt_pk_bf16_f32 v109, v104, v105
	global_store_dwordx4 v[2:3], v[106:109], off offset:256
	v_lshl_add_u64 v[2:3], v[2:3], 0, s[4:5]
	s_waitcnt vmcnt(15)
; #define PG8_GAS __attribute__((address_space(1)))
; __device__ __forceinline__ unsigned cvtpk(float lo, float hi) { f32x2 v = {lo, hi}; bf16x2_t b = __builtin_convertvector(v, bf16x2_t); return __builtin_bit_cast(unsigned, b); }
;     __device__ __forceinline__ void operator()(const f32x4 (&acc)[2][2][4][2], const Unit& u, int wr, int wc, int fr, int fq) const {
;     ...
;                     else { const u32x4 w = __builtin_nontemporal_load((const PG8_GAS u32x4*)(baseb + off + bj * HALF));
;                         b0 = (f32x4){__uint_as_float(w.x << 16), __uint_as_float(w.x & 0xffff0000u), __uint_as_float(w.y << 16), __uint_as_float(w.y & 0xffff0000u)};
;                         b1 = (f32x4){__uint_as_float(w.z << 16), __uint_as_float(w.z & 0xffff0000u), __uint_as_float(w.w << 16), __uint_as_float(w.w & 0xffff0000u)}; }
;                     const f32x4 o0 = b0 + gv[bj][0] * acc[ai][bj][m][0], o1 = b1 + gv[bj][1] * acc[ai][bj][m][1];
;                     u32x4 w; w.x = cvtpk(o0[0], o0[1]); w.y = cvtpk(o0[2], o0[3]); w.z = cvtpk(o1[0], o1[1]); w.w = cvtpk(o1[2], o1[3]);
;                     __builtin_nontemporal_store(w, (PG8_GAS u32x4*)(out + off + bj * HALF));
	v_lshlrev_b32_e32 v180, 16, v188
	v_and_b32_e32 v181, 0xffff0000, v188
	v_pk_fma_f32 v[98:99], v[98:99], v[148:149], v[180:181]
	v_lshlrev_b32_e32 v188, 16, v189
	v_and_b32_e32 v189, 0xffff0000, v189
	v_pk_fma_f32 v[100:101], v[100:101], v[146:147], v[188:189]
	v_lshlrev_b32_e32 v180, 16, v190
	v_and_b32_e32 v181, 0xffff0000, v190
	v_pk_fma_f32 v[94:95], v[94:95], v[144:145], v[180:181]
	v_lshlrev_b32_e32 v190, 16, v191
	v_and_b32_e32 v191, 0xffff0000, v191
	v_pk_fma_f32 v[96:97], v[96:97], v[142:143], v[190:191]
	v_cvt_pk_bf16_f32 v98, v98, v99
	v_cvt_pk_bf16_f32 v99, v100, v101
	v_cvt_pk_bf16_f32 v100, v94, v95
	v_cvt_pk_bf16_f32 v101, v96, v97
	global_store_dwordx4 v[2:3], v[98:101], off
	s_waitcnt vmcnt(15)
	v_lshlrev_b32_e32 v180, 16, v192
	v_and_b32_e32 v181, 0xffff0000, v192
	v_pk_fma_f32 v[90:91], v[90:91], v[140:141], v[180:181]
	v_lshlrev_b32_e32 v192, 16, v193
	v_and_b32_e32 v193, 0xffff0000, v193
	v_pk_fma_f32 v[92:93], v[92:93], v[138:139], v[192:193]
	v_lshlrev_b32_e32 v180, 16, v194
	v_and_b32_e32 v181, 0xffff0000, v194
	v_pk_fma_f32 v[86:87], v[86:87], v[136:137], v[180:181]
	v_lshlrev_b32_e32 v194, 16, v195
	v_and_b32_e32 v195, 0xffff0000, v195
	v_pk_fma_f32 v[88:89], v[88:89], v[134:135], v[194:195]
	v_cvt_pk_bf16_f32 v90, v90, v91
	v_cvt_pk_bf16_f32 v91, v92, v93
	v_cvt_pk_bf16_f32 v92, v86, v87
	v_cvt_pk_bf16_f32 v93, v88, v89
	global_store_dwordx4 v[2:3], v[90:93], off offset:256
	v_lshl_add_u64 v[2:3], v[2:3], 0, s[4:5]
	s_waitcnt vmcnt(15)
	v_lshlrev_b32_e32 v180, 16, v208
	v_and_b32_e32 v181, 0xffff0000, v208
	v_pk_fma_f32 v[82:83], v[82:83], v[148:149], v[180:181]
	v_lshlrev_b32_e32 v208, 16, v209
	v_and_b32_e32 v209, 0xffff0000, v209
	v_pk_fma_f32 v[84:85], v[84:85], v[146:147], v[208:209]
	v_lshlrev_b32_e32 v180, 16, v210
	v_and_b32_e32 v181, 0xffff0000, v210
	v_pk_fma_f32 v[78:79], v[78:79], v[144:145], v[180:181]
	v_lshlrev_b32_e32 v210, 16, v211
	v_and_b32_e32 v211, 0xffff0000, v211
	v_pk_fma_f32 v[80:81], v[80:81], v[142:143], v[210:211]
	v_cvt_pk_bf16_f32 v82, v82, v83
	v_cvt_pk_bf16_f32 v83, v84, v85
	v_cvt_pk_bf16_f32 v84, v78, v79
	v_cvt_pk_bf16_f32 v85, v80, v81
	global_store_dwordx4 v[2:3], v[82:85], off
	s_waitcnt vmcnt(15)
	v_lshlrev_b32_e32 v180, 16, v226
	v_and_b32_e32 v181, 0xffff0000, v226
	v_pk_fma_f32 v[74:75], v[74:75], v[140:141], v[180:181]
	v_lshlrev_b32_e32 v226, 16, v227
	v_and_b32_e32 v227, 0xffff0000, v227
	v_pk_fma_f32 v[76:77], v[76:77], v[138:139], v[226:227]
	v_lshlrev_b32_e32 v180, 16, v228
	v_and_b32_e32 v181, 0xffff0000, v228
	v_pk_fma_f32 v[70:71], v[70:71], v[136:137], v[180:181]
	v_lshlrev_b32_e32 v228, 16, v229
	v_and_b32_e32 v229, 0xffff0000, v229
	v_pk_fma_f32 v[72:73], v[72:73], v[134:135], v[228:229]
	v_cvt_pk_bf16_f32 v74, v74, v75
	v_cvt_pk_bf16_f32 v75, v76, v77
	v_cvt_pk_bf16_f32 v76, v70, v71
	v_cvt_pk_bf16_f32 v77, v72, v73
	global_store_dwordx4 v[2:3], v[74:77], off offset:256
	v_lshl_add_u64 v[2:3], v[2:3], 0, vcc
	s_waitcnt vmcnt(15)
	v_lshlrev_b32_e32 v180, 16, v230
	v_and_b32_e32 v181, 0xffff0000, v230
	v_pk_fma_f32 v[66:67], v[66:67], v[148:149], v[180:181]
	v_lshlrev_b32_e32 v230, 16, v231
	v_and_b32_e32 v231, 0xffff0000, v231
	v_pk_fma_f32 v[68:69], v[68:69], v[146:147], v[230:231]
	v_lshlrev_b32_e32 v180, 16, v232
	v_and_b32_e32 v181, 0xffff0000, v232
	v_pk_fma_f32 v[62:63], v[62:63], v[144:145], v[180:181]
	v_lshlrev_b32_e32 v232, 16, v233
	v_and_b32_e32 v233, 0xffff0000, v233
	v_pk_fma_f32 v[64:65], v[64:65], v[142:143], v[232:233]
	v_cvt_pk_bf16_f32 v66, v66, v67
	v_cvt_pk_bf16_f32 v67, v68, v69
	v_cvt_pk_bf16_f32 v68, v62, v63
	v_cvt_pk_bf16_f32 v69, v64, v65
	global_store_dwordx4 v[2:3], v[66:69], off
	s_waitcnt vmcnt(15)
	v_lshlrev_b32_e32 v180, 16, v234
	v_and_b32_e32 v181, 0xffff0000, v234
	v_pk_fma_f32 v[58:59], v[58:59], v[140:141], v[180:181]
	v_lshlrev_b32_e32 v234, 16, v235
	v_and_b32_e32 v235, 0xffff0000, v235
	v_pk_fma_f32 v[60:61], v[60:61], v[138:139], v[234:235]
	v_lshlrev_b32_e32 v180, 16, v236
	v_and_b32_e32 v181, 0xffff0000, v236
	v_pk_fma_f32 v[54:55], v[54:55], v[136:137], v[180:181]
	v_lshlrev_b32_e32 v236, 16, v237
	v_and_b32_e32 v237, 0xffff0000, v237
	v_pk_fma_f32 v[56:57], v[56:57], v[134:135], v[236:237]
	v_cvt_pk_bf16_f32 v58, v58, v59
	v_cvt_pk_bf16_f32 v59, v60, v61
	v_cvt_pk_bf16_f32 v60, v54, v55
	v_cvt_pk_bf16_f32 v61, v56, v57
	global_store_dwordx4 v[2:3], v[58:61], off offset:256
	v_lshl_add_u64 v[2:3], v[2:3], 0, s[4:5]
	s_waitcnt vmcnt(15)
; #define PG8_GAS __attribute__((address_space(1)))
; __device__ __forceinline__ unsigned cvtpk(float lo, float hi) { f32x2 v = {lo, hi}; bf16x2_t b = __builtin_convertvector(v, bf16x2_t); return __builtin_bit_cast(unsigned, b); }
;     __device__ __forceinline__ void operator()(const f32x4 (&acc)[2][2][4][2], const Unit& u, int wr, int wc, int fr, int fq) const {
;     ...
;                     else { const u32x4 w = __builtin_nontemporal_load((const PG8_GAS u32x4*)(baseb + off + bj * HALF));
;                         b0 = (f32x4){__uint_as_float(w.x << 16), __uint_as_float(w.x & 0xffff0000u), __uint_as_float(w.y << 16), __uint_as_float(w.y & 0xffff0000u)};
;                         b1 = (f32x4){__uint_as_float(w.z << 16), __uint_as_float(w.z & 0xffff0000u), __uint_as_float(w.w << 16), __uint_as_float(w.w & 0xffff0000u)}; }
;                     const f32x4 o0 = b0 + gv[bj][0] * acc[ai][bj][m][0], o1 = b1 + gv[bj][1] * acc[ai][bj][m][1];
;                     u32x4 w; w.x = cvtpk(o0[0], o0[1]); w.y = cvtpk(o0[2], o0[3]); w.z = cvtpk(o1[0], o1[1]); w.w = cvtpk(o1[2], o1[3]);
;                     __builtin_nontemporal_store(w, (PG8_GAS u32x4*)(out + off + bj * HALF));
	v_lshlrev_b32_e32 v180, 16, v238
	v_and_b32_e32 v181, 0xffff0000, v238
	v_pk_fma_f32 v[50:51], v[50:51], v[148:149], v[180:181]
	v_lshlrev_b32_e32 v238, 16, v239
	v_and_b32_e32 v239, 0xffff0000, v239
	v_pk_fma_f32 v[52:53], v[52:53], v[146:147], v[238:239]
	v_lshlrev_b32_e32 v180, 16, v240
	v_and_b32_e32 v181, 0xffff0000, v240
	v_pk_fma_f32 v[46:47], v[46:47], v[144:145], v[180:181]
	v_lshlrev_b32_e32 v240, 16, v241
	v_and_b32_e32 v241, 0xffff0000, v241
	v_pk_fma_f32 v[48:49], v[48:49], v[142:143], v[240:241]
	v_cvt_pk_bf16_f32 v50, v50, v51
	v_cvt_pk_bf16_f32 v51, v52, v53
	v_cvt_pk_bf16_f32 v52, v46, v47
	v_cvt_pk_bf16_f32 v53, v48, v49
	global_store_dwordx4 v[2:3], v[50:53], off
	s_waitcnt vmcnt(15)
	v_lshlrev_b32_e32 v180, 16, v242
	v_and_b32_e32 v181, 0xffff0000, v242
	v_pk_fma_f32 v[42:43], v[42:43], v[140:141], v[180:181]
	v_lshlrev_b32_e32 v242, 16, v243
	v_and_b32_e32 v243, 0xffff0000, v243
	v_pk_fma_f32 v[44:45], v[44:45], v[138:139], v[242:243]
	v_lshlrev_b32_e32 v180, 16, v244
	v_and_b32_e32 v181, 0xffff0000, v244
	v_pk_fma_f32 v[38:39], v[38:39], v[136:137], v[180:181]
	v_lshlrev_b32_e32 v244, 16, v245
	v_and_b32_e32 v245, 0xffff0000, v245
	v_pk_fma_f32 v[40:41], v[40:41], v[134:135], v[244:245]
	v_cvt_pk_bf16_f32 v42, v42, v43
	v_cvt_pk_bf16_f32 v43, v44, v45
	v_cvt_pk_bf16_f32 v44, v38, v39
	v_cvt_pk_bf16_f32 v45, v40, v41
	global_store_dwordx4 v[2:3], v[42:45], off offset:256
	v_lshl_add_u64 v[2:3], v[2:3], 0, s[4:5]
	s_waitcnt vmcnt(15)
	v_lshlrev_b32_e32 v180, 16, v246
	v_and_b32_e32 v181, 0xffff0000, v246
	v_pk_fma_f32 v[34:35], v[34:35], v[148:149], v[180:181]
	v_lshlrev_b32_e32 v246, 16, v247
	v_and_b32_e32 v247, 0xffff0000, v247
	v_pk_fma_f32 v[36:37], v[36:37], v[146:147], v[246:247]
	v_lshlrev_b32_e32 v180, 16, v248
	v_and_b32_e32 v181, 0xffff0000, v248
	v_pk_fma_f32 v[30:31], v[30:31], v[144:145], v[180:181]
	v_lshlrev_b32_e32 v248, 16, v249
	v_and_b32_e32 v249, 0xffff0000, v249
	v_pk_fma_f32 v[32:33], v[32:33], v[142:143], v[248:249]
	v_cvt_pk_bf16_f32 v34, v34, v35
	v_cvt_pk_bf16_f32 v35, v36, v37
	v_cvt_pk_bf16_f32 v36, v30, v31
	v_cvt_pk_bf16_f32 v37, v32, v33
	global_store_dwordx4 v[2:3], v[34:37], off
	s_waitcnt vmcnt(15)
	v_lshlrev_b32_e32 v180, 16, v250
	v_and_b32_e32 v181, 0xffff0000, v250
	v_pk_fma_f32 v[26:27], v[26:27], v[140:141], v[180:181]
	v_lshlrev_b32_e32 v250, 16, v251
	v_and_b32_e32 v251, 0xffff0000, v251
	v_pk_fma_f32 v[28:29], v[28:29], v[138:139], v[250:251]
	v_lshlrev_b32_e32 v180, 16, v252
	v_and_b32_e32 v181, 0xffff0000, v252
	v_pk_fma_f32 v[22:23], v[22:23], v[136:137], v[180:181]
	v_lshlrev_b32_e32 v252, 16, v253
	v_and_b32_e32 v253, 0xffff0000, v253
	v_pk_fma_f32 v[24:25], v[24:25], v[134:135], v[252:253]
	v_cvt_pk_bf16_f32 v26, v26, v27
	v_cvt_pk_bf16_f32 v27, v28, v29
	v_cvt_pk_bf16_f32 v28, v22, v23
	v_cvt_pk_bf16_f32 v29, v24, v25
	global_store_dwordx4 v[2:3], v[26:29], off offset:256
	v_lshl_add_u64 v[2:3], v[2:3], 0, s[4:5]
	s_waitcnt vmcnt(15)
	v_lshlrev_b32_e32 v180, 16, v150
	v_and_b32_e32 v181, 0xffff0000, v150
	v_pk_fma_f32 v[18:19], v[18:19], v[148:149], v[180:181]
	v_lshlrev_b32_e32 v150, 16, v151
	v_and_b32_e32 v151, 0xffff0000, v151
	v_pk_fma_f32 v[20:21], v[20:21], v[146:147], v[150:151]
	v_lshlrev_b32_e32 v180, 16, v152
	v_and_b32_e32 v181, 0xffff0000, v152
	v_pk_fma_f32 v[14:15], v[14:15], v[144:145], v[180:181]
	v_lshlrev_b32_e32 v152, 16, v153
	v_and_b32_e32 v153, 0xffff0000, v153
	v_pk_fma_f32 v[16:17], v[16:17], v[142:143], v[152:153]
	v_cvt_pk_bf16_f32 v18, v18, v19
	v_cvt_pk_bf16_f32 v19, v20, v21
	v_cvt_pk_bf16_f32 v20, v14, v15
	v_cvt_pk_bf16_f32 v21, v16, v17
	global_store_dwordx4 v[2:3], v[18:21], off
	s_waitcnt vmcnt(15)
	v_lshlrev_b32_e32 v180, 16, v126
	v_and_b32_e32 v181, 0xffff0000, v126
	v_pk_fma_f32 v[10:11], v[10:11], v[140:141], v[180:181]
	v_lshlrev_b32_e32 v126, 16, v127
	v_and_b32_e32 v127, 0xffff0000, v127
	v_pk_fma_f32 v[12:13], v[12:13], v[138:139], v[126:127]
	v_lshlrev_b32_e32 v180, 16, v128
	v_and_b32_e32 v181, 0xffff0000, v128
	v_pk_fma_f32 v[6:7], v[6:7], v[136:137], v[180:181]
	v_lshlrev_b32_e32 v128, 16, v129
	v_and_b32_e32 v129, 0xffff0000, v129
	v_pk_fma_f32 v[8:9], v[8:9], v[134:135], v[128:129]
	v_cvt_pk_bf16_f32 v10, v10, v11
	v_cvt_pk_bf16_f32 v11, v12, v13
	v_cvt_pk_bf16_f32 v12, v6, v7
	v_cvt_pk_bf16_f32 v13, v8, v9
	s_and_b64 vcc, exec, s[6:7]
	s_mov_b64 s[4:5], -1
	global_store_dwordx4 v[2:3], v[10:13], off offset:256
